# speedup vs baseline: 1.0111x; 1.0002x over previous
; #define LAS __attribute__((address_space(3)))
; template <int LDQ, int LDK, int LDV, int LDO>
; __device__ __forceinline__ void attn256_body(const int tid, const bf16_t* __restrict__ Qb, const bf16_t* __restrict__ Kh, const bf16_t* __restrict__ Vh, bf16_t* __restrict__ Ob, int seq, char* lds, LAS unsigned char* ldsl) {
;     const int wid = __builtin_amdgcn_readfirstlane(tid >> 6), lane = tid & 63, r32 = lane & 31, hi = lane >> 5;
;     float* wsf = (float*)(lds + A2_SCR) + wid * 64; float* li_l = wsf; float* al_l = wsf + 32;
;     float m_reg = -1e30f, l_reg = 0; f32x16 o[8] = {}; bf16x8 qr[8];
;     unsigned kof[2], vof[4];
; #pragma unroll
;     for (int i = 0; i < 2; ++i) { const int q = (i * 8 + wid) * 64 + lane, row = q >> 4, chunk = (q & 15) ^ (row & 7); kof[i] = (unsigned)(row * LDK + chunk * 8) * 2u; }
; #pragma unroll
;     for (int i = 0; i < 4; ++i) { const int q = (i * 8 + wid) * 64 + lane, half = q >> 10, qq = q & 1023, sub = qq >> 5, kk = (sub >> 2) * 8 + ((qq >> 2) & 7), c = (sub & 3) * 32 + (qq & 3) * 8;
; __device__ __forceinline__ void mix_phase(const int tid0, const P& p, int l, char* lds, const int per_q, const int cl) {
;     ...
;         const int xq = item >> 9, idx = item & 511;
;         if (idx < 12) { mlstm_item(tid, p, xq * 12 + idx, lds); }
;         else if (idx >= 108) {
;             const int t = xq * 258 + (idx - 108);
;             if (t < CT_UP) convert_tile(tid, (float*)lds, p.in[18] + (size_t)cl * DM * DFF, p.in[19] + (size_t)cl * DM * DFF, p.in[17] + (size_t)cl * DM, (bf16_t*)(p.ws + WS_WUP2), DM, DFF, 1, t);
;             else convert_tile(tid, (float*)lds, p.in[20] + (size_t)cl * DFF * DM, nullptr, nullptr, (bf16_t*)(p.ws + WS_WDN2), DFF, DM, 0, t - CT_UP);
;             __syncthreads();
;         }
;         else {
;             const int g = xq * 6 + ((idx - 12) >> 4), qblk = (idx - 12) & 15, comp = g & 1, head = (g >> 1) & 3, b = g >> 3;
;             const bf16_t* Q = qka + (size_t)(b * SEQ + qblk * 256) * 2048 + head * 256 + comp * 128;
;             const bf16_t* Kp = qka + (size_t)(b * SEQ) * 2048 + 1024 + head * 256 + comp * 128;
;             const bf16_t* Vp = z + (size_t)(b * SEQ) * ZLD + 6144 + head * 256;
;             bf16_t* O = z + (size_t)(b * SEQ + qblk * 256) * ZLD + 4096 + comp * 1024 + head * 256;
;             attn256_body<2048, 2048, ZLD, ZLD>(tid, Q, Kp, Vp, O, SEQ, lds, (LAS unsigned char*)lds);
.LBB0_130:
	s_or_b64 exec, exec, s[0:1]
	v_mov_b32_e32 v0, s33
	s_waitcnt lgkmcnt(0)
	s_barrier
	ds_read_b32 v0, v0
	s_waitcnt lgkmcnt(0)
	s_barrier
	v_cmp_gt_i32_e32 vcc, 0, v0
	v_readfirstlane_b32 s8, v0
	s_cbranch_vccnz .LBB0_142
	s_lshr_b32 s9, s8, 9
	s_and_b32 s14, s8, 0x1ff
	s_cmp_gt_u32 s14, 11
	s_mov_b64 s[0:1], -1
	s_cbranch_scc0 .LBB0_155
	s_cmpk_lt_u32 s14, 0x6c
	s_cbranch_scc0 .LBB0_146
	s_add_i32 s1, s14, -12
	s_mul_i32 s0, s9, 6
	s_lshr_b32 s4, s1, 4
	s_add_i32 s25, s4, s0
	s_lshl_b32 s0, s25, 9
	s_and_b32 s4, s0, 0x7ffff000
	s_lshl_b32 s0, s1, 8
	s_and_b32 s0, s0, 0xf00
	s_or_b32 s30, s4, s0
	s_bfe_u32 s15, s1, 0x10004
	s_lshl_b64 s[0:1], s[30:31], 12
	s_add_u32 s0, s54, s0
	s_addc_u32 s1, s67, s1
	s_lshl_b32 s5, s25, 7
	s_and_b32 s16, s5, 0x300
	s_lshl_b32 s17, s16, 1
	s_add_u32 s0, s0, s17
	s_addc_u32 s1, s1, 0
	s_lshl_b32 s24, s15, 8
	s_add_u32 s0, s0, s24
	s_mov_b32 s5, s31
	s_addc_u32 s1, s1, 0
	s_lshl_b64 s[6:7], s[4:5], 12
	s_add_u32 s5, s54, s6
	s_addc_u32 s21, s67, s7
	s_add_u32 s5, s5, s17
	s_addc_u32 s21, s21, 0
	s_add_u32 s22, s5, s24
	s_addc_u32 s23, s21, 0
	s_mul_i32 s36, s4, 0x3800
	s_mul_hi_u32 s28, s4, 0x3800
	s_add_u32 s4, s93, s36
	v_readfirstlane_b32 s21, v208
	s_addc_u32 s5, s66, s28
	s_movk_i32 s38, 0xffc0
	v_mov_b32_e32 v0, s21
	s_add_u32 s4, s4, s17
	v_bfi_b32 v2, s38, v0, v209
	s_addc_u32 s5, s5, 0
	v_and_b32_e32 v3, 15, v209
	v_ashrrev_i32_e32 v0, 4, v2
	v_add_u32_e32 v2, 0x200, v2
	s_add_u32 s4, s4, 0x3000
	v_bitop3_b32 v4, v0, v3, 15 bitop3:0x6c
	v_lshlrev_b32_e32 v0, 12, v0
	v_ashrrev_i32_e32 v2, 4, v2
	s_addc_u32 s5, s5, 0
	s_and_b32 s37, s21, 0xffffffc0
	v_lshl_or_b32 v0, v4, 4, v0
	v_bitop3_b32 v3, v2, v3, 15 bitop3:0x6c
	v_lshlrev_b32_e32 v2, 12, v2
	v_lshrrev_b32_e32 v4, 1, v208
	s_lshr_b32 s46, s21, 5
	v_lshl_or_b32 v2, v3, 4, v2
	v_bfe_u32 v3, v208, 2, 2
	v_and_b32_e32 v4, 8, v4
	s_and_b32 s46, s46, 4
	s_add_i32 s47, s37, 0x200
	v_lshlrev_b32_e32 v8, 3, v209
	v_or3_b32 v3, v4, v3, s46
	s_lshr_b32 s48, s47, 4
	s_lshl_b32 s17, s37, 2
	s_and_b32 s38, s21, 64
	v_and_b32_e32 v7, 32, v209
	v_and_b32_e32 v9, 24, v8
	s_lshr_b32 s46, s21, 4
	v_and_or_b32 v12, s48, 48, v3
	s_ashr_i32 s47, s47, 3
	s_add_i32 s48, s21, 0x400
	s_addk_i32 s37, 0x600
	v_or3_b32 v4, v9, v7, s38
	v_and_or_b32 v10, s46, 48, v3
	s_ashr_i32 s46, s21, 3
	s_and_b32 s47, s47, 0xffffff80
	s_ashr_i32 s48, s48, 3
	s_lshr_b32 s49, s37, 4
	s_ashr_i32 s37, s37, 3
	s_and_b32 s46, s46, 0xffffff80
	v_mul_u32_u24_e32 v13, 0x1c00, v12
	v_or_b32_e32 v14, s47, v4
	s_and_b32 s48, s48, 0xffffff80
	v_and_or_b32 v15, s49, 48, v3
	s_and_b32 s49, s37, 0xffffff80
	s_ashr_i32 s37, s21, 6
	v_mul_u32_u24_e32 v5, 0x1c00, v10
	v_or_b32_e32 v11, s46, v4
	v_add_lshl_u32 v13, v14, v13, 1
	v_or_b32_e32 v14, s48, v4
	v_mul_u32_u24_e32 v3, 0x1c00, v15
	v_or_b32_e32 v4, s49, v4
	s_lshl_b32 s21, s37, 10
	v_add_lshl_u32 v11, v11, v5, 1
	v_add_lshl_u32 v14, v14, v5, 1
	v_add_lshl_u32 v16, v4, v3, 1
	s_add_i32 s21, s21, 0
	v_lshl_add_u64 v[4:5], s[22:23], 0, v[0:1]
	s_mov_b64 s[56:57], 0x800
	v_lshl_add_u64 v[4:5], v[4:5], 0, s[56:57]
	s_mov_b32 m0, s21
	v_mov_b32_e32 v3, v1
	global_load_lds_dwordx4 v[4:5], off
	v_lshl_add_u64 v[4:5], s[22:23], 0, v[2:3]
	v_and_b32_e32 v211, 31, v209
	v_lshl_add_u64 v[4:5], v[4:5], 0, s[56:57]
	s_add_i32 m0, s21, 0x2000
	s_lshl_b32 s22, s37, 5
	global_load_lds_dwordx4 v[4:5], off
	s_add_i32 m0, s21, 0x8000
	v_or_b32_e32 v4, s22, v211
	global_load_lds_dwordx4 v11, s[4:5]
	s_add_i32 m0, s21, 0xa000
	v_ashrrev_i32_e32 v5, 31, v4
	v_bfe_u32 v210, v209, 5, 1
	global_load_lds_dwordx4 v13, s[4:5]
	s_add_i32 m0, s21, 0xc000
	v_lshlrev_b64 v[4:5], 12, v[4:5]
	global_load_lds_dwordx4 v14, s[4:5]
	s_add_i32 m0, s21, 0xe000
	v_lshl_add_u64 v[4:5], s[0:1], 0, v[4:5]
	v_lshlrev_b32_e32 v194, 4, v210
	v_mov_b32_e32 v195, v1
	global_load_lds_dwordx4 v16, s[4:5]
	v_lshl_add_u64 v[4:5], v[4:5], 0, v[194:195]
	global_load_dwordx4 v[162:165], v[4:5], off
	global_load_dwordx4 v[166:169], v[4:5], off offset:32
	global_load_dwordx4 v[170:173], v[4:5], off offset:64
	global_load_dwordx4 v[174:177], v[4:5], off offset:96
	global_load_dwordx4 v[178:181], v[4:5], off offset:128
	global_load_dwordx4 v[182:185], v[4:5], off offset:160
	global_load_dwordx4 v[186:189], v[4:5], off offset:192
	global_load_dwordx4 v[190:193], v[4:5], off offset:224
	v_lshlrev_b32_e32 v4, 4, v209
	v_and_b32_e32 v13, 0xf0, v4
	s_movk_i32 s0, 0x60
; __device__ __forceinline__ int v_rd_base(int lane) { return ((lane & 3) << 3) | (((lane >> 2) & 3) << 6) | (((lane >> 4) & 1) << 5) | (((lane >> 5) & 1) << 8); }
; __device__ __forceinline__ void qkt(f32x16& p0, f32x16& p1, const char* Ks, const bf16x8* qr, int r32, int hi) {
;     ...
;     for (int d0 = 0; d0 < 8; ++d0) { const int cb = (d0 * 16 + hi * 8) * 2;
;         bf16x8 b0 = *reinterpret_cast<const bf16x8*>(Ks + KSWZ(r32, cb));
;         bf16x8 b1 = *reinterpret_cast<const bf16x8*>(Ks + KSWZ(32 + r32, cb));
; template <int LDQ, int LDK, int LDV, int LDO>
; __device__ __forceinline__ void attn256_body(const int tid, const bf16_t* __restrict__ Qb, const bf16_t* __restrict__ Kh, const bf16_t* __restrict__ Vh, bf16_t* __restrict__ Ob, int seq, char* lds, LAS unsigned char* ldsl) {
;     const int wid = __builtin_amdgcn_readfirstlane(tid >> 6), lane = tid & 63, r32 = lane & 31, hi = lane >> 5;
;     float* wsf = (float*)(lds + A2_SCR) + wid * 64; float* li_l = wsf; float* al_l = wsf + 32;
;     float m_reg = -1e30f, l_reg = 0; f32x16 o[8] = {}; bf16x8 qr[8];
;     unsigned kof[2], vof[4];
; #pragma unroll
;     for (int i = 0; i < 2; ++i) { const int q = (i * 8 + wid) * 64 + lane, row = q >> 4, chunk = (q & 15) ^ (row & 7); kof[i] = (unsigned)(row * LDK + chunk * 8) * 2u; }
; #pragma unroll
;     for (int i = 0; i < 4; ++i) { const int q = (i * 8 + wid) * 64 + lane, half = q >> 10, qq = q & 1023, sub = qq >> 5, kk = (sub >> 2) * 8 + ((qq >> 2) & 7), c = (sub & 3) * 32 + (qq & 3) * 8;
;         const int k = (kk & ~0xC) | ((kk & 4) << 1) | ((kk & 8) >> 1); vof[i] = (unsigned)(k * LDV + half * 128 + c) * 2u; }
;     ...
;     A2_ISSUE(0, 0);
;     { const bf16_t* Qw = Qb + (long)(wid * 32 + r32) * LDQ + hi * 8;
; #pragma unroll
;       for (int d0 = 0; d0 < 8; ++d0) qr[d0] = *reinterpret_cast<const bf16x8*>(Qw + d0 * 16); }
;     const int vb0 = (int)(uintptr_t)(lds + A2_VOFF) + v_rd_base(lane);
;     const int NT = seq / 64;
;     constexpr float C = ATT_SCALE * 1.4426950408889634f;
;     for (int j = 0; j < NT; ++j) {
	v_bitop3_b32 v215, v194, v13, s0 bitop3:0x36
	s_movk_i32 s0, 0xa0
	s_add_i32 s17, s17, 0
	v_bitop3_b32 v218, v194, v13, s0 bitop3:0x36
	s_movk_i32 s0, 0xc0
	s_add_i32 s17, s17, 0x18000
	v_lshlrev_b32_e32 v11, 1, v209
	v_bitop3_b32 v219, v194, v13, s0 bitop3:0x36
	s_movk_i32 s0, 0xe0
	v_and_b32_e32 v11, 32, v11
	v_bitop3_b32 v220, v194, v13, s0 bitop3:0x36
	s_movk_i32 s0, 0x118
	s_cmp_lg_u32 0, -1
	v_and_b32_e32 v5, 0xc0, v4
	v_xor_b32_e32 v212, v194, v13
	v_and_or_b32 v4, v8, s0, v11
	s_cselect_b32 s0, 0, 0
	s_add_i32 s0, s0, 0x8000
	v_add3_u32 v221, v5, s0, v4
	s_lshl_b32 s0, s25, 8
	s_or_b32 s25, s38, s46
	v_mov_b32_e32 v4, s25
	s_movk_i32 s46, 0x1c00
	s_and_b32 s0, s0, 0x600
	v_mad_u32_u24 v4, v10, s46, v4
	v_readlane_b32 s25, v255, 17
	v_or3_b32 v4, v4, v7, v9
	s_add_u32 s36, s25, s36
	v_lshlrev_b32_e32 v4, 1, v4
	v_mov_b32_e32 v5, v1
	s_addc_u32 s37, s65, s28
	s_or_b32 s25, s38, s47
	v_lshl_add_u64 v[196:197], s[36:37], 0, v[4:5]
	v_mov_b32_e32 v4, s25
	v_mad_u32_u24 v4, v12, s46, v4
	v_or3_b32 v4, v4, v7, v9
	v_lshlrev_b32_e32 v4, 1, v4
	s_or_b32 s25, s38, s48
	v_lshl_add_u64 v[198:199], s[36:37], 0, v[4:5]
	v_mov_b32_e32 v4, s25
	v_mad_u32_u24 v4, v10, s46, v4
	v_or3_b32 v4, v4, v7, v9
	v_lshlrev_b32_e32 v4, 1, v4
	s_or_b32 s25, s38, s49
	v_lshl_add_u64 v[200:201], s[36:37], 0, v[4:5]
	v_mov_b32_e32 v4, s25
	v_mad_u32_u24 v4, v15, s46, v4
	s_or_b32 s6, s6, s24
	v_or3_b32 v4, v4, v7, v9
	s_add_u32 s6, s92, s6
	v_and_b32_e32 v6, 63, v209
	v_lshlrev_b32_e32 v4, 1, v4
	s_addc_u32 s7, s51, s7
	v_mov_b32_e32 v14, v1
	v_mov_b32_e32 v15, v1
	v_bitop3_b32 v213, v194, v13, 32 bitop3:0x36
	v_bitop3_b32 v214, v194, v13, 64 bitop3:0x36
	v_bitop3_b32 v216, v194, v13, s88 bitop3:0x36
	v_cmp_gt_u32_e64 s[4:5], 32, v6
	v_lshl_add_u64 v[202:203], s[36:37], 0, v[4:5]
	v_lshl_add_u64 v[204:205], s[6:7], 0, v[2:3]
	v_lshl_add_u64 v[206:207], s[6:7], 0, v[0:1]
	v_mov_b32_e32 v0, v1
	v_mov_b32_e32 v2, v1
	v_mov_b32_e32 v4, v1
	v_mov_b32_e32 v6, v1
	v_mov_b32_e32 v7, v1
	v_mov_b32_e32 v8, v1
	v_mov_b32_e32 v9, v1
	v_mov_b32_e32 v10, v1
	v_mov_b32_e32 v11, v1
	v_mov_b32_e32 v12, v1
	v_mov_b32_e32 v13, v1
	v_mov_b64_e32 v[128:129], v[14:15]
	v_mov_b64_e32 v[112:113], v[14:15]
	v_mov_b64_e32 v[96:97], v[14:15]
	v_mov_b64_e32 v[80:81], v[14:15]
	v_mov_b64_e32 v[64:65], v[14:15]
	v_mov_b64_e32 v[48:49], v[14:15]
	v_mov_b64_e32 v[32:33], v[14:15]
	v_mov_b64_e32 v[126:127], v[12:13]
	v_mov_b64_e32 v[124:125], v[10:11]
	v_mov_b64_e32 v[122:123], v[8:9]
	v_mov_b64_e32 v[120:121], v[6:7]
	v_mov_b64_e32 v[118:119], v[4:5]
	v_mov_b64_e32 v[116:117], v[2:3]
	v_mov_b64_e32 v[114:115], v[0:1]
	v_mov_b64_e32 v[110:111], v[12:13]
	v_mov_b64_e32 v[108:109], v[10:11]
	v_mov_b64_e32 v[106:107], v[8:9]
	v_mov_b64_e32 v[104:105], v[6:7]
	v_mov_b64_e32 v[102:103], v[4:5]
	v_mov_b64_e32 v[100:101], v[2:3]
	v_mov_b64_e32 v[98:99], v[0:1]
	v_mov_b64_e32 v[94:95], v[12:13]
	v_mov_b64_e32 v[92:93], v[10:11]
	v_mov_b64_e32 v[90:91], v[8:9]
	v_mov_b64_e32 v[88:89], v[6:7]
	v_mov_b64_e32 v[86:87], v[4:5]
	v_mov_b64_e32 v[84:85], v[2:3]
	v_mov_b64_e32 v[82:83], v[0:1]
	v_mov_b64_e32 v[78:79], v[12:13]
	v_mov_b64_e32 v[76:77], v[10:11]
	v_mov_b64_e32 v[74:75], v[8:9]
	v_mov_b64_e32 v[72:73], v[6:7]
	v_mov_b64_e32 v[70:71], v[4:5]
	v_mov_b64_e32 v[68:69], v[2:3]
	v_mov_b64_e32 v[66:67], v[0:1]
	v_mov_b64_e32 v[62:63], v[12:13]
	v_mov_b64_e32 v[60:61], v[10:11]
	v_mov_b64_e32 v[58:59], v[8:9]
	v_mov_b64_e32 v[56:57], v[6:7]
	v_mov_b64_e32 v[54:55], v[4:5]
	v_mov_b64_e32 v[52:53], v[2:3]
	v_mov_b64_e32 v[50:51], v[0:1]
	v_mov_b64_e32 v[46:47], v[12:13]
	v_mov_b64_e32 v[44:45], v[10:11]
	v_mov_b64_e32 v[42:43], v[8:9]
	v_mov_b64_e32 v[40:41], v[6:7]
	v_mov_b64_e32 v[38:39], v[4:5]
	v_mov_b64_e32 v[36:37], v[2:3]
	v_mov_b64_e32 v[34:35], v[0:1]
	v_mov_b64_e32 v[30:31], v[12:13]
	v_mov_b64_e32 v[28:29], v[10:11]
	v_mov_b64_e32 v[26:27], v[8:9]
	v_mov_b64_e32 v[24:25], v[6:7]
	v_mov_b64_e32 v[22:23], v[4:5]
	v_mov_b64_e32 v[20:21], v[2:3]
	v_mov_b64_e32 v[18:19], v[0:1]
	v_mov_b64_e32 v[16:17], v[14:15]
	v_lshlrev_b32_e32 v195, 8, v211
	v_lshl_add_u32 v217, v211, 2, s17
	s_mov_b32 s23, 0
	s_mov_b32 s1, s31
	v_mov_b32_e32 v223, 0
	v_mov_b32_e32 v222, 0xf149f2ca
	v_mov_b64_e32 v[14:15], v[12:13]
	v_mov_b64_e32 v[12:13], v[10:11]
	v_mov_b64_e32 v[10:11], v[8:9]
	v_mov_b64_e32 v[8:9], v[6:7]
	v_mov_b64_e32 v[6:7], v[4:5]
	v_mov_b64_e32 v[4:5], v[2:3]
	v_mov_b64_e32 v[2:3], v[0:1]
	s_waitcnt vmcnt(0)
